# combined: cost-weighted MFMA/VALU spacing in the PV half plus packed-f32 row sums
# baseline (speedup 1.0000x reference)
.LBB0_381:
	s_barrier
	s_mulk_i32 s3, 0x2400
	v_add3_u32 v190, v143, s3, v142
	v_add_u32_e32 v191, 0x6800, v190
	v_add_u32_e32 v192, 0x7a00, v190
	ds_read2_b64 v[194:197], v191 offset1:2
	ds_read2_b64 v[198:201], v192 offset1:2
	ds_read2_b64 v[202:205], v191 offset0:4 offset1:6
	ds_read2_b64 v[206:209], v192 offset0:4 offset1:6
	ds_read2_b64 v[210:213], v191 offset0:8 offset1:10
	ds_read2_b64 v[214:217], v192 offset0:8 offset1:10
	ds_read2_b64 v[218:221], v191 offset0:12 offset1:14
	ds_read2_b64 v[222:225], v192 offset0:12 offset1:14
	v_exp_f32_e32 v32, v32
	v_exp_f32_e32 v33, v33
	v_exp_f32_e32 v34, v34
	v_exp_f32_e32 v35, v35
	v_exp_f32_e32 v36, v36
	v_exp_f32_e32 v37, v37
	v_exp_f32_e32 v38, v38
	v_exp_f32_e32 v39, v39
	v_cvt_pk_bf16_f32 v160, v32, v33
	v_cvt_pk_bf16_f32 v161, v34, v35
	v_cvt_pk_bf16_f32 v162, v36, v37
	v_cvt_pk_bf16_f32 v163, v38, v39
	v_pk_add_f32 v[168:169], v[32:33], v[34:35]
	v_pk_add_f32 v[168:169], v[168:169], v[36:37]
	v_pk_add_f32 v[168:169], v[168:169], v[38:39]
	s_waitcnt lgkmcnt(6)
	v_mfma_f32_32x32x16_bf16 v[16:31], v[194:197], v[160:163], v[16:31]
	v_exp_f32_e32 v40, v40
	v_exp_f32_e32 v41, v41
	v_exp_f32_e32 v42, v42
	v_exp_f32_e32 v43, v43
	v_exp_f32_e32 v44, v44
	v_exp_f32_e32 v45, v45
	v_exp_f32_e32 v46, v46
	v_exp_f32_e32 v47, v47
	v_mfma_f32_32x32x16_bf16 v[0:15], v[198:201], v[160:163], v[0:15]
	v_cvt_pk_bf16_f32 v164, v40, v41
	v_cvt_pk_bf16_f32 v165, v42, v43
	v_cvt_pk_bf16_f32 v166, v44, v45
	v_cvt_pk_bf16_f32 v167, v46, v47
	v_pk_add_f32 v[168:169], v[168:169], v[40:41]
	v_pk_add_f32 v[168:169], v[168:169], v[42:43]
	v_pk_add_f32 v[168:169], v[168:169], v[44:45]
	v_pk_add_f32 v[168:169], v[168:169], v[46:47]
	s_waitcnt lgkmcnt(4)
	v_mfma_f32_32x32x16_bf16 v[16:31], v[202:205], v[164:167], v[16:31]
	v_exp_f32_e32 v48, v48
	v_exp_f32_e32 v49, v49
	v_exp_f32_e32 v50, v50
	v_exp_f32_e32 v51, v51
	v_exp_f32_e32 v52, v52
	v_exp_f32_e32 v53, v53
	v_exp_f32_e32 v54, v54
	v_exp_f32_e32 v55, v55
	v_mfma_f32_32x32x16_bf16 v[0:15], v[206:209], v[164:167], v[0:15]
	v_cvt_pk_bf16_f32 v160, v48, v49
	v_cvt_pk_bf16_f32 v161, v50, v51
	v_cvt_pk_bf16_f32 v162, v52, v53
	v_cvt_pk_bf16_f32 v163, v54, v55
	v_pk_add_f32 v[168:169], v[168:169], v[48:49]
	v_pk_add_f32 v[168:169], v[168:169], v[50:51]
	v_pk_add_f32 v[168:169], v[168:169], v[52:53]
	v_pk_add_f32 v[168:169], v[168:169], v[54:55]
	s_waitcnt lgkmcnt(2)
	v_mfma_f32_32x32x16_bf16 v[16:31], v[210:213], v[160:163], v[16:31]
	v_exp_f32_e32 v56, v56
	v_exp_f32_e32 v57, v57
	v_exp_f32_e32 v58, v58
	v_exp_f32_e32 v59, v59
	v_exp_f32_e32 v60, v60
	v_exp_f32_e32 v61, v61
	v_exp_f32_e32 v62, v62
	v_exp_f32_e32 v63, v63
	v_mfma_f32_32x32x16_bf16 v[0:15], v[214:217], v[160:163], v[0:15]
	v_cvt_pk_bf16_f32 v164, v56, v57
	v_cvt_pk_bf16_f32 v165, v58, v59
	v_cvt_pk_bf16_f32 v166, v60, v61
	v_cvt_pk_bf16_f32 v167, v62, v63
	v_pk_add_f32 v[168:169], v[168:169], v[56:57]
	v_pk_add_f32 v[168:169], v[168:169], v[58:59]
	v_pk_add_f32 v[168:169], v[168:169], v[60:61]
	v_pk_add_f32 v[168:169], v[168:169], v[62:63]
	v_add_f32_e32 v168, v168, v169
	v_add_f32_e32 v119, v119, v168
	s_add_i32 s1, s1, 64
	s_cmpk_lg_i32 s1, 0x11c0
	s_waitcnt lgkmcnt(0)
	s_barrier
	v_mfma_f32_32x32x16_bf16 v[16:31], v[218:221], v[164:167], v[16:31]
	v_mfma_f32_32x32x16_bf16 v[0:15], v[222:225], v[164:167], v[0:15]
	s_cbranch_scc0 .LBB0_383
	s_mov_b32 s3, s2
	s_branch .LBB0_377
